# v29 + fox loops: next-tile global loads issued at the previous iteration tail (after commit ds_writes, before lgkmcnt(0)+barrier) instead of at the loop head
# baseline (speedup 1.0000x reference)
; #define LAS __attribute__((address_space(3)))
; DI float bf2f(unsigned h) { return __uint_as_float(h << 16); }
; DI void fox_unit(const bf16* PR, const float* AUX, const float* bfp, bf16* MIX, char* sm, int b, int h, int qb, bool do_cs) {
;     ...
;     const float cref = cbuf[q0];
;     const bf16* Kb = PR + rb * NP + C_FK + 64 * h; const bf16* Vb = PR + rb * NP + C_FV + 64 * h;
;     float m = MINIT, l = 0.f; f32x16 o0, o1;
; #pragma unroll
;     for (int i = 0; i < 16; ++i) { o0[i] = 0.f; o1[i] = 0.f; }
;     unsigned z_ = 0u; asm volatile("" : "+v"(z_)); u32x4 kr, vr, ar = {z_, z_, z_, z_};
;     const int wq0 = q0 + 32 * wid;
;     u32x4 zpre[4];
;     const bf16* zrow0 = PR + (rb + wq0) * NP + C_FZ + 64 * h;
;     float q1 = 0.f;
; #pragma unroll
;     for (int d0 = 0; d0 < 4; ++d0)
; #pragma unroll
;         for (int j = 0; j < 8; ++j) q1 += fabsf(bf2f((unsigned)(unsigned short)qr[d0][j]));
;     q1 += __shfl_xor(q1, 32);
;     volatile LAS unsigned* kmx = (volatile LAS unsigned*)(sm + L_MISC) + 32;
;     for (int it_ = -1, nt_ = (4 * qb + 4); it_ < nt_; ++it_) {
;         const bool more_ = it_ + 1 < nt_;
;         if (!more_) {
; #pragma unroll
;             for (int j = 0; j < 4; ++j) zpre[j] = *(const u32x4*)(zrow0 + (size_t)((lane >> 3) + 8 * j) * NP + 8 * (lane & 7));
;         }
;         if (more_) { const int kt = nt_ - 2 - it_; { kv_issue(Kb + (size_t)(64 * kt) * NP, Vb + (size_t)(64 * kt) * NP, NP, wid, lane, kr, vr);
.LBB0_339:
	s_lshl_b32 s18, s27, 2
	s_add_i32 s30, s18, 0
	s_add_i32 s30, s30, 0x13580
	s_and_saveexec_b64 s[18:19], s[2:3]
	v_mov_b32_e32 v0, s30
	ds_write_b32 v0, v176
	s_or_b64 exec, exec, s[18:19]
	v_cndmask_b32_e64 v7, 0, v182, s[6:7]
	s_ashr_i32 s7, s28, 31
	s_add_u32 s6, s14, s28
	s_addc_u32 s7, s15, s7
	s_lshl_b32 s31, s13, 2
	s_add_i32 s31, s31, 4
	s_lshl_b64 s[18:19], s[6:7], 13
	s_add_u32 s13, s86, s18
	s_addc_u32 s19, s87, s19
	s_add_u32 s18, s13, s8
	s_addc_u32 s19, s19, s9
	v_and_b32_e32 v0, 0x70, v194
	s_waitcnt lgkmcnt(2)
	v_add_f32_e32 v161, v3, v4
	v_lshl_add_u64 v[4:5], s[18:19], 0, v[0:1]
	v_lshlrev_b32_e32 v0, 1, v171
	v_and_b32_e32 v199, 32, v0
	v_lshlrev_b32_e32 v0, 10, v171
	v_and_b32_e32 v0, 0xe000, v0
	v_lshl_add_u64 v[4:5], v[4:5], 0, v[0:1]
	v_xor_b32_e32 v0, 1, v181
	v_cmp_lt_i32_e32 vcc, v0, v2
	s_mov_b64 s[10:11], 0x900
	v_lshl_add_u64 v[162:163], v[4:5], 0, s[10:11]
	v_cndmask_b32_e32 v0, v181, v0, vcc
	v_lshlrev_b32_e32 v188, 2, v0
	v_xor_b32_e32 v0, 2, v181
	v_cmp_lt_i32_e32 vcc, v0, v2
	s_mov_b64 s[10:11], 0x10900
	v_lshl_add_u64 v[164:165], v[4:5], 0, s[10:11]
	v_cndmask_b32_e32 v0, v181, v0, vcc
	v_lshlrev_b32_e32 v189, 2, v0
	v_xor_b32_e32 v0, 4, v181
	v_cmp_lt_i32_e32 vcc, v0, v2
	s_mov_b64 s[10:11], 0x20900
	v_lshl_add_u64 v[166:167], v[4:5], 0, s[10:11]
	v_cndmask_b32_e32 v0, v181, v0, vcc
	v_lshlrev_b32_e32 v190, 2, v0
	v_xor_b32_e32 v0, 8, v181
	v_cmp_lt_i32_e32 vcc, v0, v2
	s_mov_b64 s[10:11], 0x30900
	v_lshl_add_u64 v[168:169], v[4:5], 0, s[10:11]
	v_cndmask_b32_e32 v0, v181, v0, vcc
	v_lshlrev_b32_e32 v191, 2, v0
	v_xor_b32_e32 v0, 16, v181
	v_cmp_lt_i32_e32 vcc, v0, v2
	s_mov_b32 s10, 0x5040100
	s_lshl_b32 s29, s12, 10
	v_cndmask_b32_e32 v0, v181, v0, vcc
	s_addk_i32 s20, 0xff40
	v_mov_b32_e32 v14, v1
	v_mov_b32_e32 v15, v1
	v_lshlrev_b32_e32 v197, 4, v6
	v_perm_b32 v111, 0, v7, v183
	v_perm_b32 v110, v7, v7, s10
	v_lshlrev_b32_e32 v192, 2, v0
	s_sub_i32 s13, 0, s29
	v_add_u32_e32 v235, s20, v6
	v_mov_b32_e32 v0, v1
	v_mov_b32_e32 v2, v1
	v_mov_b32_e32 v3, v1
	v_mov_b32_e32 v4, v1
	v_mov_b32_e32 v5, v1
	v_mov_b32_e32 v6, v1
	v_mov_b32_e32 v7, v1
	v_mov_b32_e32 v8, v1
	v_mov_b32_e32 v9, v1
	v_mov_b32_e32 v10, v1
	v_mov_b32_e32 v11, v1
	v_mov_b32_e32 v12, v1
	v_mov_b32_e32 v13, v1
	v_mov_b64_e32 v[32:33], v[14:15]
	v_lshlrev_b32_e32 v201, 4, v171
	v_lshlrev_b32_e32 v203, 2, v193
	s_pack_ll_b32_b16 s10, 0, 0
	s_add_i32 s35, s13, 0xae00
	s_lshl_b32 s13, s12, 8
	v_mov_b64_e32 v[30:31], v[12:13]
	v_mov_b64_e32 v[28:29], v[10:11]
	v_mov_b64_e32 v[26:27], v[8:9]
	v_mov_b64_e32 v[24:25], v[6:7]
	v_mov_b64_e32 v[22:23], v[4:5]
	v_mov_b64_e32 v[20:21], v[2:3]
	v_mov_b64_e32 v[18:19], v[0:1]
	v_mov_b64_e32 v[16:17], v[14:15]
	s_or_b32 s34, s28, 31
	v_lshlrev_b32_e32 v198, 10, v193
	v_lshlrev_b32_e32 v200, 8, v193
	v_and_b32_e32 v202, 0xc0, v201
	v_or_b32_e32 v204, 32, v203
	v_or_b32_e32 v205, 33, v203
	v_or_b32_e32 v206, 2, v203
	v_or_b32_e32 v207, 34, v203
	v_or_b32_e32 v208, 3, v203
	v_or_b32_e32 v209, 35, v203
	v_or_b32_e32 v210, 8, v203
	v_or_b32_e32 v211, 40, v203
	v_or_b32_e32 v212, 9, v203
	v_or_b32_e32 v213, 41, v203
	v_or_b32_e32 v214, 10, v203
	v_or_b32_e32 v215, 42, v203
	v_or_b32_e32 v216, 11, v203
	v_or_b32_e32 v217, 43, v203
	v_or_b32_e32 v218, 16, v203
	v_or_b32_e32 v219, 48, v203
	v_or_b32_e32 v220, 17, v203
	v_or_b32_e32 v221, 49, v203
	v_or_b32_e32 v222, 18, v203
	v_or_b32_e32 v223, 50, v203
	v_or_b32_e32 v224, 19, v203
	v_or_b32_e32 v225, 51, v203
	v_or_b32_e32 v226, 24, v203
	v_or_b32_e32 v227, 56, v203
	v_or_b32_e32 v228, 25, v203
	v_or_b32_e32 v229, 57, v203
	v_or_b32_e32 v230, 26, v203
	v_or_b32_e32 v231, 58, v203
	v_or_b32_e32 v232, 27, v203
	v_or_b32_e32 v233, 59, v203
	v_mov_b32_e32 v112, s10
	v_mov_b32_e32 v113, s10
	v_lshlrev_b32_e32 v234, 2, v171
	s_sub_i32 s18, 0x780, s13
	s_mov_b32 s100, s18
	s_ashr_i32 s101, s18, 31
	s_lshl_b64 s[100:101], s[100:101], 13
	v_lshl_add_u64 v[248:249], v[146:147], 0, s[100:101]
	v_lshl_add_u64 v[250:251], v[158:159], 0, s[100:101]
	global_load_dwordx4 v[90:93], v[248:249], off offset:768
	global_load_dwordx4 v[94:97], v[250:251], off offset:1536
	s_mov_b32 s33, 0
	v_mov_b32_e32 v236, 0
	v_mov_b32_e32 v237, 0xee013f39
	v_mov_b64_e32 v[14:15], v[12:13]
	v_mov_b64_e32 v[12:13], v[10:11]
	v_mov_b64_e32 v[10:11], v[8:9]
	v_mov_b64_e32 v[8:9], v[6:7]
	v_mov_b64_e32 v[6:7], v[4:5]
	v_mov_b64_e32 v[4:5], v[2:3]
	v_mov_b64_e32 v[2:3], v[0:1]
	s_waitcnt lgkmcnt(0)
	s_barrier

; DI unsigned f2bf(float f) { unsigned u = __float_as_uint(f); return (u + 0x7fffu + ((u >> 16) & 1u)) >> 16; }
; DI float bf2f(unsigned h) { return __uint_as_float(h << 16); }
; DI u32x4 split3(float a) {
;     const unsigned h = f2bf(a); const float r1 = a - bf2f(h); const unsigned m = f2bf(r1); const unsigned l = f2bf(r1 - bf2f(m));
;     u32x4 r; r.x = h | (m << 16); r.y = l; r.z = 0u; r.w = 0u; return r;
; }
; DI void fox_unit(const bf16* PR, const float* AUX, const float* bfp, bf16* MIX, char* sm, int b, int h, int qb, bool do_cs) {
;     ...
;         if (more_) { const int kt = nt_ - 2 - it_; { kv_issue(Kb + (size_t)(64 * kt) * NP, Vb + (size_t)(64 * kt) * NP, NP, wid, lane, kr, vr);
;           if (wid == 0) ar = split3(8.f * (cref - cbuf[64 * kt + lane])); } }
.LBB0_344:
	s_andn2_b64 vcc, exec, s[22:23]
	s_cbranch_vccnz .LBB0_347
	s_and_b64 vcc, exec, s[4:5]
	s_cbranch_vccnz .LBB0_348
	v_add_u32_e32 v0, s35, v234
	ds_read_b32 v0, v0
	v_mov_b32_e32 v84, 0
	s_waitcnt lgkmcnt(0)
	v_sub_f32_e32 v0, v195, v0
	v_mul_f32_e32 v34, 0x41000000, v0
	v_bfe_u32 v35, v34, 16, 1
	v_add3_u32 v34, v34, v35, s93
	v_and_b32_e32 v35, 0xffff0000, v34
	v_fma_f32 v0, v0, s59, -v35
	v_bfe_u32 v35, v0, 16, 1
	v_add3_u32 v35, v0, v35, s93
	v_and_b32_e32 v35, 0xffff0000, v35
	v_sub_f32_e32 v0, v0, v35
	v_or_b32_sdwa v82, v35, v34 dst_sel:DWORD dst_unused:UNUSED_PAD src0_sel:DWORD src1_sel:WORD_1
	v_bfe_u32 v34, v0, 16, 1
	v_add3_u32 v0, v0, v34, s93
	v_lshrrev_b32_e32 v83, 16, v0
	s_branch .LBB0_348

; DI void fox_unit(const bf16* PR, const float* AUX, const float* bfp, bf16* MIX, char* sm, int b, int h, int qb, bool do_cs) {
;     ...
;         if (more_) { kv_commit(sm + ((it_ + 1) & 1) * STG, tid, wid, lane, kr, vr, ar);
;             const bool far_ = 64 * (nt_ - 2 - it_) + 63 + 384 < q0;
;             unsigned mk = 0x7f80u;
;             if (far_) { mk = (kr.x & 0x7fffu); { const unsigned t1 = (kr.x >> 16) & 0x7fffu; mk = t1 > mk ? t1 : mk; }
;             { const unsigned t0 = kr.y & 0x7fffu, t1 = (kr.y >> 16) & 0x7fffu; mk = t0 > mk ? t0 : mk; mk = t1 > mk ? t1 : mk; }
;             { const unsigned t0 = kr.z & 0x7fffu, t1 = (kr.z >> 16) & 0x7fffu; mk = t0 > mk ? t0 : mk; mk = t1 > mk ? t1 : mk; }
;             { const unsigned t0 = kr.w & 0x7fffu, t1 = (kr.w >> 16) & 0x7fffu; mk = t0 > mk ? t0 : mk; mk = t1 > mk ? t1 : mk; }
; #pragma unroll
;             for (int o = 1; o < 64; o <<= 1) { const unsigned y = (unsigned)__shfl_xor((int)mk, o); mk = y > mk ? y : mk; } }
;             if (lane == 0) kmx[((it_ + 1) & 1) * 8 + wid] = mk; }
;         __syncthreads();
;     }
.LBB0_363:
	s_addk_i32 s35, 0xff00
	s_sub_i32 s18, s18, 64
	s_add_i32 s100, s36, 1
	s_cmp_lt_u32 s100, s31
	s_cbranch_scc0 .Lpf1_skip
	s_mov_b32 s100, s18
	s_ashr_i32 s101, s18, 31
	s_lshl_b64 s[100:101], s[100:101], 13
	v_lshl_add_u64 v[248:249], v[146:147], 0, s[100:101]
	v_lshl_add_u64 v[250:251], v[158:159], 0, s[100:101]
	global_load_dwordx4 v[90:93], v[248:249], off offset:768
	global_load_dwordx4 v[94:97], v[250:251], off offset:1536
.Lpf1_skip:
	s_cmp_lg_u32 s31, s36
	v_add_u32_e32 v235, 64, v235
	s_waitcnt lgkmcnt(0)
	s_barrier
	s_cbranch_scc0 .LBB0_367
	s_mov_b32 s33, s36
	s_branch .LBB0_342

; #define LAS __attribute__((address_space(3)))
; DI float bf2f(unsigned h) { return __uint_as_float(h << 16); }
; DI void fox_unit(const bf16* PR, const float* AUX, const float* bfp, bf16* MIX, char* sm, int b, int h, int qb, bool do_cs) {
;     ...
;     const float cref = cbuf[q0];
;     const bf16* Kb = PR + rb * NP + C_FK + 64 * h; const bf16* Vb = PR + rb * NP + C_FV + 64 * h;
;     float m = MINIT, l = 0.f; f32x16 o0, o1;
; #pragma unroll
;     for (int i = 0; i < 16; ++i) { o0[i] = 0.f; o1[i] = 0.f; }
;     unsigned z_ = 0u; asm volatile("" : "+v"(z_)); u32x4 kr, vr, ar = {z_, z_, z_, z_};
;     const int wq0 = q0 + 32 * wid;
;     u32x4 zpre[4];
;     const bf16* zrow0 = PR + (rb + wq0) * NP + C_FZ + 64 * h;
;     float q1 = 0.f;
; #pragma unroll
;     for (int d0 = 0; d0 < 4; ++d0)
; #pragma unroll
;         for (int j = 0; j < 8; ++j) q1 += fabsf(bf2f((unsigned)(unsigned short)qr[d0][j]));
;     q1 += __shfl_xor(q1, 32);
;     volatile LAS unsigned* kmx = (volatile LAS unsigned*)(sm + L_MISC) + 32;
;     for (int it_ = -1, nt_ = (4 * qb + 4); it_ < nt_; ++it_) {
;         const bool more_ = it_ + 1 < nt_;
;         if (!more_) {
; #pragma unroll
;             for (int j = 0; j < 4; ++j) zpre[j] = *(const u32x4*)(zrow0 + (size_t)((lane >> 3) + 8 * j) * NP + 8 * (lane & 7));
;         }
;         if (more_) { const int kt = nt_ - 2 - it_; { kv_issue(Kb + (size_t)(64 * kt) * NP, Vb + (size_t)(64 * kt) * NP, NP, wid, lane, kr, vr);
.LBB0_384:
	s_lshl_b32 s12, s12, 2
	s_add_i32 s12, s12, 4
	s_cmp_eq_u32 s12, 0
	s_waitcnt lgkmcnt(0)
	s_barrier
	s_cbranch_scc1 .LBB0_411
	v_mov_b32_e32 v11, v1
	v_lshl_add_u64 v[2:3], v[8:9], 0, v[10:11]
	s_mov_b64 s[10:11], 0x900
	v_lshl_add_u64 v[164:165], v[2:3], 0, s[10:11]
	s_mov_b64 s[10:11], 0x10900
	v_lshl_add_u64 v[166:167], v[2:3], 0, s[10:11]
	s_mov_b64 s[10:11], 0x20900
	v_lshlrev_b32_e32 v0, 1, v195
	v_cmp_gt_u32_e32 vcc, 32, v195
	v_lshl_add_u64 v[168:169], v[2:3], 0, s[10:11]
	s_mov_b64 s[10:11], 0x30900
	v_and_b32_e32 v200, 32, v0
	v_cndmask_b32_e32 v0, 0, v182, vcc
	v_add_f32_e32 v163, v13, v14
	v_lshl_add_u64 v[170:171], v[2:3], 0, s[10:11]
	s_mov_b32 s10, 0x5040100
	s_addk_i32 s26, 0xff40
	v_mov_b32_e32 v14, v1
	v_mov_b32_e32 v15, v1
	v_lshlrev_b32_e32 v198, 4, v12
	v_perm_b32 v113, 0, v0, v183
	v_perm_b32 v112, v0, v0, s10
	v_add_u32_e32 v236, s26, v12
	v_mov_b32_e32 v0, v1
	v_mov_b32_e32 v2, v1
	v_mov_b32_e32 v3, v1
	v_mov_b32_e32 v4, v1
	v_mov_b32_e32 v5, v1
	v_mov_b32_e32 v6, v1
	v_mov_b32_e32 v7, v1
	v_mov_b32_e32 v8, v1
	v_mov_b32_e32 v9, v1
	v_mov_b32_e32 v10, v1
	v_mov_b32_e32 v12, v1
	v_mov_b32_e32 v13, v1
	v_mov_b64_e32 v[32:33], v[14:15]
	v_lshlrev_b32_e32 v202, 4, v195
	v_lshlrev_b32_e32 v204, 2, v194
	s_pack_ll_b32_b16 s10, 0, 0
	s_add_i32 s14, s29, 0
	v_mov_b64_e32 v[30:31], v[12:13]
	v_mov_b64_e32 v[28:29], v[10:11]
	v_mov_b64_e32 v[26:27], v[8:9]
	v_mov_b64_e32 v[24:25], v[6:7]
	v_mov_b64_e32 v[22:23], v[4:5]
	v_mov_b64_e32 v[20:21], v[2:3]
	v_mov_b64_e32 v[18:19], v[0:1]
	v_mov_b64_e32 v[16:17], v[14:15]
	s_or_b32 s21, s19, 31
	v_lshlrev_b32_e32 v199, 10, v194
	v_lshlrev_b32_e32 v201, 8, v194
	v_and_b32_e32 v203, 0xc0, v202
	v_or_b32_e32 v205, 32, v204
	v_or_b32_e32 v206, 33, v204
	v_or_b32_e32 v207, 2, v204
	v_or_b32_e32 v208, 34, v204
	v_or_b32_e32 v209, 3, v204
	v_or_b32_e32 v210, 35, v204
	v_or_b32_e32 v211, 8, v204
	v_or_b32_e32 v212, 40, v204
	v_or_b32_e32 v213, 9, v204
	v_or_b32_e32 v214, 41, v204
	v_or_b32_e32 v215, 10, v204
	v_or_b32_e32 v216, 42, v204
	v_or_b32_e32 v217, 11, v204
	v_or_b32_e32 v218, 43, v204
	v_or_b32_e32 v219, 16, v204
	v_or_b32_e32 v220, 48, v204
	v_or_b32_e32 v221, 17, v204
	v_or_b32_e32 v222, 49, v204
	v_or_b32_e32 v223, 18, v204
	v_or_b32_e32 v224, 50, v204
	v_or_b32_e32 v225, 19, v204
	v_or_b32_e32 v226, 51, v204
	v_or_b32_e32 v227, 24, v204
	v_or_b32_e32 v228, 56, v204
	v_or_b32_e32 v229, 25, v204
	v_or_b32_e32 v230, 57, v204
	v_or_b32_e32 v231, 26, v204
	v_or_b32_e32 v232, 58, v204
	v_or_b32_e32 v233, 27, v204
	v_or_b32_e32 v234, 59, v204
	v_mov_b32_e32 v114, s10
	v_mov_b32_e32 v115, s10
	v_lshlrev_b32_e32 v235, 2, v195
	s_add_i32 s22, s14, 0x9200
	s_add_i32 s23, s13, 0x23f
	s_add_i32 s100, s23, 0xfffffe41
	s_ashr_i32 s101, s100, 31
	s_lshl_b64 s[100:101], s[100:101], 13
	v_lshl_add_u64 v[248:249], v[158:159], 0, s[100:101]
	v_lshl_add_u64 v[250:251], v[160:161], 0, s[100:101]
	global_load_dwordx4 v[104:107], v[248:249], off offset:768
	global_load_dwordx4 v[100:103], v[250:251], off offset:1536
	s_mov_b32 s26, 0
	v_mov_b32_e32 v34, 0
	v_mov_b32_e32 v237, 0xee013f39
	v_mov_b64_e32 v[14:15], v[12:13]
	v_mov_b64_e32 v[12:13], v[10:11]
	v_mov_b64_e32 v[10:11], v[8:9]
	v_mov_b64_e32 v[8:9], v[6:7]
	v_mov_b64_e32 v[6:7], v[4:5]
	v_mov_b64_e32 v[4:5], v[2:3]
	v_mov_b64_e32 v[2:3], v[0:1]

; DI unsigned f2bf(float f) { unsigned u = __float_as_uint(f); return (u + 0x7fffu + ((u >> 16) & 1u)) >> 16; }
; DI float bf2f(unsigned h) { return __uint_as_float(h << 16); }
; DI u32x4 split3(float a) {
;     const unsigned h = f2bf(a); const float r1 = a - bf2f(h); const unsigned m = f2bf(r1); const unsigned l = f2bf(r1 - bf2f(m));
;     u32x4 r; r.x = h | (m << 16); r.y = l; r.z = 0u; r.w = 0u; return r;
; }
; DI void fox_unit(const bf16* PR, const float* AUX, const float* bfp, bf16* MIX, char* sm, int b, int h, int qb, bool do_cs) {
;     ...
;         if (more_) { const int kt = nt_ - 2 - it_; { kv_issue(Kb + (size_t)(64 * kt) * NP, Vb + (size_t)(64 * kt) * NP, NP, wid, lane, kr, vr);
;           if (wid == 0) ar = split3(8.f * (cref - cbuf[64 * kt + lane])); } }
.LBB0_388:
	s_andn2_b64 vcc, exec, s[16:17]
	s_cbranch_vccnz .LBB0_391
	s_and_b64 vcc, exec, s[2:3]
	s_cbranch_vccnz .LBB0_392
	v_add_u32_e32 v0, s22, v235
	ds_read_b32 v0, v0
	v_mov_b32_e32 v110, 0
	s_waitcnt lgkmcnt(0)
	v_sub_f32_e32 v0, v35, v0
	v_mul_f32_e32 v36, 0x41000000, v0
	v_bfe_u32 v37, v36, 16, 1
	v_add3_u32 v36, v36, v37, s93
	v_and_b32_e32 v37, 0xffff0000, v36
	v_fma_f32 v0, v0, s59, -v37
	v_bfe_u32 v37, v0, 16, 1
	v_add3_u32 v37, v0, v37, s93
	v_and_b32_e32 v37, 0xffff0000, v37
	v_sub_f32_e32 v0, v0, v37
	v_or_b32_sdwa v108, v37, v36 dst_sel:DWORD dst_unused:UNUSED_PAD src0_sel:DWORD src1_sel:WORD_1
	v_bfe_u32 v36, v0, 16, 1
	v_add3_u32 v0, v0, v36, s93
	v_lshrrev_b32_e32 v109, 16, v0
	s_branch .LBB0_392

; DI void fox_unit(const bf16* PR, const float* AUX, const float* bfp, bf16* MIX, char* sm, int b, int h, int qb, bool do_cs) {
;     ...
;         if (more_) { kv_commit(sm + ((it_ + 1) & 1) * STG, tid, wid, lane, kr, vr, ar);
;             const bool far_ = 64 * (nt_ - 2 - it_) + 63 + 384 < q0;
;             unsigned mk = 0x7f80u;
;             if (far_) { mk = (kr.x & 0x7fffu); { const unsigned t1 = (kr.x >> 16) & 0x7fffu; mk = t1 > mk ? t1 : mk; }
;             { const unsigned t0 = kr.y & 0x7fffu, t1 = (kr.y >> 16) & 0x7fffu; mk = t0 > mk ? t0 : mk; mk = t1 > mk ? t1 : mk; }
;             { const unsigned t0 = kr.z & 0x7fffu, t1 = (kr.z >> 16) & 0x7fffu; mk = t0 > mk ? t0 : mk; mk = t1 > mk ? t1 : mk; }
;             { const unsigned t0 = kr.w & 0x7fffu, t1 = (kr.w >> 16) & 0x7fffu; mk = t0 > mk ? t0 : mk; mk = t1 > mk ? t1 : mk; }
; #pragma unroll
;             for (int o = 1; o < 64; o <<= 1) { const unsigned y = (unsigned)__shfl_xor((int)mk, o); mk = y > mk ? y : mk; } }
;             if (lane == 0) kmx[((it_ + 1) & 1) * 8 + wid] = mk; }
;         __syncthreads();
;     }
.LBB0_407:
	s_addk_i32 s22, 0xff00
	s_sub_i32 s23, s23, 64
	s_add_i32 s100, s25, 1
	s_cmp_lt_i32 s100, s12
	s_cbranch_scc0 .Lpf2_skip
	s_add_i32 s100, s23, 0xfffffe41
	s_ashr_i32 s101, s100, 31
	s_lshl_b64 s[100:101], s[100:101], 13
	v_lshl_add_u64 v[248:249], v[158:159], 0, s[100:101]
	v_lshl_add_u64 v[250:251], v[160:161], 0, s[100:101]
	global_load_dwordx4 v[104:107], v[248:249], off offset:768
	global_load_dwordx4 v[100:103], v[250:251], off offset:1536
.Lpf2_skip:
	s_cmp_lg_u32 s12, s25
	v_add_u32_e32 v236, 64, v236
	s_waitcnt lgkmcnt(0)
	s_barrier
	s_cbranch_scc0 .LBB0_412
	s_mov_b32 s26, s25
	s_branch .LBB0_386
